# nsa-sel-qk-mfma-interleaved-into-softmax
# speedup vs baseline: 1.0091x; 1.0020x over previous
; #define LAS __attribute__((address_space(3)))
; __device__ __forceinline__ float ex2(float x) { return __builtin_amdgcn_exp2f(x); }
; __device__ __forceinline__ v16f mfma32(v8s a, v8s b, v16f c) { return __builtin_amdgcn_mfma_f32_32x32x16_bf16(a, b, c, 0, 0, 0); }
; __device__ __forceinline__ float max3f(float a, float b, float c) { return __builtin_fmaxf(__builtin_fmaxf(a, b), c); }
;     __device__ __forceinline__ bool rowok(int t) const { return ((t < 32 ? (mlo >> t) : (mhi >> (t - 32))) & 1u) != 0u; }
;     __device__ __forceinline__ bool rowok(int t, int sub) const { const unsigned lo = sub ? mloB : mloA, hh = sub ? mhiB : mhiA; return ((t < 32 ? (lo >> t) : (hh >> (t - 32))) & 1u) != 0u; }
; __device__ __forceinline__ void k_load(const LAS unsigned char* Kt, v8s (&kf)[8], int r32, int hi) {
;     const LAS unsigned char* kb = Kt + r32 * KP + hi * 16;
; #pragma unroll
;     for (int s = 0; s < 4; ++s) { kf[2 * s] = *(const LAS v8s*)(kb + s * 32); kf[2 * s + 1] = *(const LAS v8s*)(kb + 32 * KP + s * 32); }
; }
; __device__ __forceinline__ void qk_mma(const v8s (&kf)[8], const v8s (&qf)[4], v16f& p0, v16f& p1) {
;     v16f z;
; #pragma unroll
;     for (int r = 0; r < 16; ++r) z[r] = 0.f;
;     p0 = z; p1 = z;
; #pragma unroll
;     for (int s = 0; s < 4; ++s) { p0 = mfma32(kf[2 * s], qf[s], p0); p1 = mfma32(kf[2 * s + 1], qf[s], p1); }
; }
; __device__ __forceinline__ void softmax_step(v16f& p0, v16f& p1, v16f (&oT)[2], float& m, float& l, bool rowok) {
;     float a = max3f(p0[0], p0[1], p1[0]), b = max3f(p0[2], p0[3], p1[1]); a = max3f(a, p1[2], p1[3]);
; #pragma unroll
;     for (int r = 4; r < 16; r += 4) { a = max3f(a, p0[r], p0[r + 1]); b = max3f(b, p0[r + 2], p0[r + 3]); a = max3f(a, p1[r], p1[r + 1]); b = max3f(b, p1[r + 2], p1[r + 3]); }
;     float mx = fmaxf(a, b);
;     mx = xhalf_max(mx);
;     if (!rowok) mx = -INFINITY;
;     float mn = m;
;     if (__any(mx > m + SM_THR)) {
;         mn = fmaxf(m, mx);
;         const float mu_ = (mn == -INFINITY) ? 0.f : mn;
;         const float alpha = ex2(m - mu_);
;         oT[0] = oT[0] * alpha; oT[1] = oT[1] * alpha; l *= alpha;
;     }
.LBB0_533:
	s_add_i32 s0, s54, 1
	s_cmp_lg_u32 s54, 2
	s_cselect_b32 s55, s0, 0
	s_cmp_gt_i32 s50, -1
	s_cselect_b64 s[24:25], -1, 0
	s_cmp_lt_i32 s50, 0
	s_cbranch_scc1 .LBB0_535
	s_mul_i32 s0, s55, 0x2400
	v_add_u32_e32 v0, s0, v198
	ds_read_b128 v[218:221], v0
	ds_read_b128 v[222:225], v0 offset:32
	ds_read_b128 v[226:229], v0 offset:4608
	ds_read_b128 v[230:233], v0 offset:4640
	ds_read_b128 v[244:247], v0 offset:64
	ds_read_b128 v[248:251], v0 offset:96
	ds_read_b128 v[208:211], v0 offset:4672
	ds_read_b128 v[212:215], v0 offset:4704
.LBB0_535:
	s_mul_i32 s0, s54, 0x2080
	v_add_u32_e32 v0, s0, v201
	ds_read_b64_tr_b16 v[174:175], v0 offset:28672
	ds_read_b64_tr_b16 v[176:177], v0 offset:29184
	ds_read_b64_tr_b16 v[166:167], v0 offset:29696
	ds_read_b64_tr_b16 v[168:169], v0 offset:30208
	ds_read_b64_tr_b16 v[170:171], v0 offset:32832
	ds_read_b64_tr_b16 v[172:173], v0 offset:33344
	ds_read_b64_tr_b16 v[162:163], v0 offset:33856
	ds_read_b64_tr_b16 v[164:165], v0 offset:34368
	ds_read_b64_tr_b16 v[178:179], v0 offset:31808
	ds_read_b64_tr_b16 v[180:181], v0 offset:32320
	ds_read_b64_tr_b16 v[158:159], v0 offset:30720
	ds_read_b64_tr_b16 v[160:161], v0 offset:31232
	ds_read_b64_tr_b16 v[182:183], v0 offset:27648
	ds_read_b64_tr_b16 v[184:185], v0 offset:28160
	ds_read_b64_tr_b16 v[154:155], v0 offset:34880
	ds_read_b64_tr_b16 v[156:157], v0 offset:35392
	s_waitcnt lgkmcnt(15)
	v_mfma_f32_32x32x16_bf16 v[114:129], v[218:221], v[130:133], 0
	v_mfma_f32_32x32x16_bf16 v[98:113], v[226:229], v[130:133], 0
	v_sub_co_u32_e64 v0, vcc, s56, 32
	v_lshrrev_b32_e32 v204, s56, v188
	v_lshrrev_b32_e32 v0, v0, v189
	v_cndmask_b32_e32 v0, v0, v204, vcc
	v_and_b32_e32 v0, 1, v0
	v_cmp_eq_u32_e64 s[0:1], 0, v0
	v_max_f32_e32 v0, v67, v67
	v_max_f32_e32 v204, v66, v66
	v_max_f32_e32 v0, v204, v0
	v_max3_f32 v204, v68, v69, v83
	v_max3_f32 v0, v0, v82, v84
	v_max3_f32 v0, v0, v85, v70
	v_max3_f32 v204, v204, v72, v73
	v_max3_f32 v0, v0, v71, v86
	v_max3_f32 v204, v204, v88, v89
	v_mfma_f32_32x32x16_bf16 v[114:129], v[222:225], v[134:137], v[114:129]
	v_max3_f32 v0, v0, v87, v74
	v_max3_f32 v204, v204, v76, v77
	v_max3_f32 v0, v0, v75, v90
	v_max3_f32 v204, v204, v92, v93
	v_max3_f32 v0, v0, v91, v78
	v_max3_f32 v204, v204, v80, v81
	v_mfma_f32_32x32x16_bf16 v[98:113], v[230:233], v[134:137], v[98:113]
	v_max3_f32 v0, v0, v79, v94
	v_max3_f32 v204, v204, v96, v97
	v_max3_f32 v0, v0, v95, v204
	v_mov_b32_e32 v204, v0
	s_nop 1
	v_permlane32_swap_b32_e32 v0, v204
	v_max_f32_e32 v204, v204, v204
	v_max_f32_e32 v0, v0, v0
	v_max_f32_e32 v0, v0, v204
	v_cndmask_b32_e64 v0, v0, v241, s[0:1]
	v_add_f32_e32 v204, 0x41800000, v217
	v_cmp_gt_f32_e32 vcc, v0, v204
	s_cbranch_vccz .LBB0_537
	v_max_f32_e32 v0, v0, v0
	v_max_f32_e32 v2, v217, v217
	v_max_f32_e32 v204, v2, v0
	v_cmp_neq_f32_e32 vcc, s76, v204
	s_nop 1
	v_cndmask_b32_e32 v0, 0, v204, vcc
	v_sub_f32_e32 v0, v217, v0
	v_exp_f32_e32 v0, v0
	v_mov_b32_e32 v217, v204
	v_pk_mul_f32 v[64:65], v[64:65], v[0:1] op_sel_hi:[1,0]
	v_pk_mul_f32 v[62:63], v[62:63], v[0:1] op_sel_hi:[1,0]
	v_pk_mul_f32 v[60:61], v[60:61], v[0:1] op_sel_hi:[1,0]
	v_pk_mul_f32 v[58:59], v[58:59], v[0:1] op_sel_hi:[1,0]
	v_pk_mul_f32 v[56:57], v[56:57], v[0:1] op_sel_hi:[1,0]
	v_pk_mul_f32 v[54:55], v[54:55], v[0:1] op_sel_hi:[1,0]
	v_pk_mul_f32 v[52:53], v[52:53], v[0:1] op_sel_hi:[1,0]
	v_pk_mul_f32 v[50:51], v[50:51], v[0:1] op_sel_hi:[1,0]
	v_pk_mul_f32 v[48:49], v[48:49], v[0:1] op_sel_hi:[1,0]
	v_pk_mul_f32 v[46:47], v[46:47], v[0:1] op_sel_hi:[1,0]
	v_pk_mul_f32 v[44:45], v[44:45], v[0:1] op_sel_hi:[1,0]
	v_pk_mul_f32 v[42:43], v[42:43], v[0:1] op_sel_hi:[1,0]
	v_pk_mul_f32 v[40:41], v[40:41], v[0:1] op_sel_hi:[1,0]
	v_pk_mul_f32 v[38:39], v[38:39], v[0:1] op_sel_hi:[1,0]
	v_pk_mul_f32 v[36:37], v[36:37], v[0:1] op_sel_hi:[1,0]
	v_pk_mul_f32 v[34:35], v[34:35], v[0:1] op_sel_hi:[1,0]
	v_mul_f32_e32 v216, v216, v0
; #define LAS __attribute__((address_space(3)))
; __device__ __forceinline__ v16f mfma32(v8s a, v8s b, v16f c) { return __builtin_amdgcn_mfma_f32_32x32x16_bf16(a, b, c, 0, 0, 0); }
; __device__ __forceinline__ void pv_mma(const v4s (&vf)[16], const v16f& p0, const v16f& p1, v16f (&oT)[2]) {
;     v4u w[4];
;     w[0] = (v4u){pkbf(p0[0], p0[1]), pkbf(p0[2], p0[3]), pkbf(p0[4], p0[5]), pkbf(p0[6], p0[7])};
;     w[1] = (v4u){pkbf(p0[8], p0[9]), pkbf(p0[10], p0[11]), pkbf(p0[12], p0[13]), pkbf(p0[14], p0[15])};
;     w[2] = (v4u){pkbf(p1[0], p1[1]), pkbf(p1[2], p1[3]), pkbf(p1[4], p1[5]), pkbf(p1[6], p1[7])};
;     w[3] = (v4u){pkbf(p1[8], p1[9]), pkbf(p1[10], p1[11]), pkbf(p1[12], p1[13]), pkbf(p1[14], p1[15])};
; #pragma unroll
;     for (int ks = 0; ks < 4; ++ks)
; #pragma unroll
;         for (int dt = 0; dt < 2; ++dt) {
;             const v4s lo = vf[4 * ks + 2 * dt], h4 = vf[4 * ks + 2 * dt + 1];
;             const v8s af = (v8s){lo[0], lo[1], lo[2], lo[3], h4[0], h4[1], h4[2], h4[3]};
;             oT[dt] = mfma32(af, __builtin_bit_cast(v8s, w[ks]), oT[dt]);
;         }
;     __device__ __forceinline__ void apply_tab(v16f& p0, v16f& p1, int t) const {
;         const LAS float* bp = tb + (NEGPAD + qpos - 64 * t - 63 - 4 * hi);
;         v16f c0, c1;
; #pragma unroll
;         for (int r = 0; r < 16; ++r) { c0[r] = bp[63 - ((r & 3) + 8 * (r >> 2))]; c1[r] = bp[31 - ((r & 3) + 8 * (r >> 2))]; }
;         p0 = p0 * C1 + c0; p1 = p1 * C1 + c1;
;     }
.LBB0_537:
	v_cmp_neq_f32_e32 vcc, s76, v217
	s_nop 1
	v_cndmask_b32_e32 v0, 0, v217, vcc
	v_cndmask_b32_e64 v6, v0, v240, s[0:1]
	v_sub_f32_e32 v2, v73, v6
	v_sub_f32_e32 v3, v72, v6
	v_sub_f32_e32 v4, v71, v6
	v_sub_f32_e32 v5, v70, v6
	v_sub_f32_e32 v15, v69, v6
	v_sub_f32_e32 v16, v68, v6
	v_sub_f32_e32 v17, v67, v6
	v_sub_f32_e32 v18, v66, v6
	v_exp_f32_e32 v66, v18
	v_exp_f32_e32 v67, v17
	v_exp_f32_e32 v68, v16
	v_exp_f32_e32 v69, v15
	v_exp_f32_e32 v70, v5
	v_exp_f32_e32 v71, v4
	v_exp_f32_e32 v72, v3
	v_exp_f32_e32 v73, v2
	v_cvt_pk_bf16_f32 v2, v66, v67
	v_cvt_pk_bf16_f32 v3, v68, v69
	v_cvt_pk_bf16_f32 v4, v70, v71
	v_cvt_pk_bf16_f32 v5, v72, v73
	v_sub_f32_e32 v7, v81, v6
	v_sub_f32_e32 v8, v80, v6
	s_waitcnt lgkmcnt(2)
	v_mfma_f32_32x32x16_bf16 v[34:49], v[182:185], v[2:5], v[34:49]
	v_sub_f32_e32 v9, v79, v6
	v_sub_f32_e32 v10, v78, v6
	v_sub_f32_e32 v11, v77, v6
	v_sub_f32_e32 v12, v76, v6
	v_mfma_f32_32x32x16_bf16 v[114:129], v[244:247], v[138:141], v[114:129]
	v_sub_f32_e32 v13, v75, v6
	v_sub_f32_e32 v14, v74, v6
	v_exp_f32_e32 v74, v14
	v_mfma_f32_32x32x16_bf16 v[50:65], v[178:181], v[2:5], v[50:65]
	v_exp_f32_e32 v75, v13
	v_exp_f32_e32 v76, v12
	v_exp_f32_e32 v77, v11
	v_exp_f32_e32 v78, v10
	v_exp_f32_e32 v79, v9
	v_mfma_f32_32x32x16_bf16 v[98:113], v[208:211], v[138:141], v[98:113]
	v_exp_f32_e32 v80, v8
	v_exp_f32_e32 v81, v7
	v_cvt_pk_bf16_f32 v2, v74, v75
	v_cvt_pk_bf16_f32 v3, v76, v77
	v_cvt_pk_bf16_f32 v4, v78, v79
	v_cvt_pk_bf16_f32 v5, v80, v81
	v_sub_f32_e32 v26, v89, v6
	v_sub_f32_e32 v27, v88, v6
	v_mfma_f32_32x32x16_bf16 v[34:49], v[174:177], v[2:5], v[34:49]
	v_sub_f32_e32 v28, v87, v6
	v_sub_f32_e32 v29, v86, v6
	v_sub_f32_e32 v15, v85, v6
	v_sub_f32_e32 v16, v84, v6
	v_mfma_f32_32x32x16_bf16 v[114:129], v[248:251], v[142:145], v[114:129]
	v_sub_f32_e32 v7, v83, v6
	v_sub_f32_e32 v8, v82, v6
	v_exp_f32_e32 v82, v8
	v_mfma_f32_32x32x16_bf16 v[50:65], v[170:173], v[2:5], v[50:65]
	v_exp_f32_e32 v83, v7
	v_exp_f32_e32 v84, v16
	v_exp_f32_e32 v85, v15
	v_exp_f32_e32 v86, v29
	v_exp_f32_e32 v87, v28
	v_mfma_f32_32x32x16_bf16 v[98:113], v[212:215], v[142:145], v[98:113]
	v_exp_f32_e32 v88, v27
	v_exp_f32_e32 v89, v26
	v_cvt_pk_bf16_f32 v2, v82, v83
	v_cvt_pk_bf16_f32 v3, v84, v85
	v_cvt_pk_bf16_f32 v4, v86, v87
	v_cvt_pk_bf16_f32 v5, v88, v89
	v_sub_f32_e32 v19, v97, v6
	v_sub_f32_e32 v20, v96, v6
	v_mfma_f32_32x32x16_bf16 v[34:49], v[166:169], v[2:5], v[34:49]
	v_sub_f32_e32 v21, v95, v6
	v_sub_f32_e32 v22, v94, v6
	v_sub_f32_e32 v23, v93, v6
	v_sub_f32_e32 v24, v92, v6
	v_sub_f32_e32 v25, v91, v6
	v_sub_f32_e32 v6, v90, v6
	v_exp_f32_e32 v90, v6
	v_mfma_f32_32x32x16_bf16 v[50:65], v[162:165], v[2:5], v[50:65]
	v_exp_f32_e32 v91, v25
	v_exp_f32_e32 v92, v24
	v_exp_f32_e32 v93, v23
	v_exp_f32_e32 v94, v22
	v_exp_f32_e32 v95, v21
	v_exp_f32_e32 v96, v20
	v_exp_f32_e32 v97, v19
	s_nop 3
	v_cvt_pk_bf16_f32 v162, v90, v91
	v_cvt_pk_bf16_f32 v163, v92, v93
	v_cvt_pk_bf16_f32 v164, v94, v95
	v_cvt_pk_bf16_f32 v165, v96, v97
	s_nop 1
	v_mfma_f32_32x32x16_bf16 v[34:49], v[158:161], v[162:165], v[34:49]
	s_andn2_b64 vcc, exec, s[24:25]
	s_waitcnt lgkmcnt(0)
	v_mfma_f32_32x32x16_bf16 v[50:65], v[154:157], v[162:165], v[50:65]
	s_cbranch_vccnz .LBB0_543
	s_lshl_b32 s24, s50, 6
	s_sub_i32 s0, s49, s24
	s_cmpk_lt_i32 s0, 0x400
	s_mov_b64 s[0:1], -1
	s_cbranch_scc0 .LBB0_540
	v_add_u32_e32 v2, s24, v200
	v_sub_u32_e32 v2, v199, v2
	v_lshl_add_u32 v18, v2, 2, s37
	v_add_u32_e32 v18, 0xd110, v18
	ds_read2_b32 v[2:3], v18 offset0:58 offset1:59
	ds_read2_b32 v[154:155], v18 offset0:26 offset1:27
	ds_read2_b32 v[4:5], v18 offset0:56 offset1:57
	ds_read2_b32 v[20:21], v18 offset0:24 offset1:25
	ds_read2_b32 v[6:7], v18 offset0:50 offset1:51
	ds_read2_b32 v[22:23], v18 offset0:18 offset1:19
	ds_read2_b32 v[8:9], v18 offset0:48 offset1:49
	ds_read2_b32 v[24:25], v18 offset0:16 offset1:17
	ds_read2_b32 v[10:11], v18 offset0:42 offset1:43
	ds_read2_b32 v[26:27], v18 offset0:10 offset1:11
	ds_read2_b32 v[12:13], v18 offset0:40 offset1:41
	ds_read2_b32 v[28:29], v18 offset0:8 offset1:9
	ds_read2_b32 v[14:15], v18 offset0:34 offset1:35
	ds_read2_b32 v[16:17], v18 offset0:32 offset1:33
	ds_read2_b32 v[30:31], v18 offset0:0 offset1:1
	ds_read2_b32 v[32:33], v18 offset0:2 offset1:3
	s_waitcnt lgkmcnt(14)
	v_pk_fma_f32 v[114:115], v[114:115], s[52:53], v[2:3] op_sel:[0,0,1] op_sel_hi:[1,0,0]
	v_pk_fma_f32 v[98:99], v[98:99], s[52:53], v[154:155] op_sel:[0,0,1] op_sel_hi:[1,0,0]
	s_waitcnt lgkmcnt(12)
	v_pk_fma_f32 v[116:117], v[116:117], s[52:53], v[4:5] op_sel:[0,0,1] op_sel_hi:[1,0,0]
	v_pk_fma_f32 v[100:101], v[100:101], s[52:53], v[20:21] op_sel:[0,0,1] op_sel_hi:[1,0,0]
	s_waitcnt lgkmcnt(10)
	v_pk_fma_f32 v[118:119], v[118:119], s[52:53], v[6:7] op_sel:[0,0,1] op_sel_hi:[1,0,0]
	v_pk_fma_f32 v[102:103], v[102:103], s[52:53], v[22:23] op_sel:[0,0,1] op_sel_hi:[1,0,0]
	s_waitcnt lgkmcnt(8)
	v_pk_fma_f32 v[120:121], v[120:121], s[52:53], v[8:9] op_sel:[0,0,1] op_sel_hi:[1,0,0]
	v_pk_fma_f32 v[104:105], v[104:105], s[52:53], v[24:25] op_sel:[0,0,1] op_sel_hi:[1,0,0]
	s_waitcnt lgkmcnt(6)
	v_pk_fma_f32 v[122:123], v[122:123], s[52:53], v[10:11] op_sel:[0,0,1] op_sel_hi:[1,0,0]
	v_pk_fma_f32 v[106:107], v[106:107], s[52:53], v[26:27] op_sel:[0,0,1] op_sel_hi:[1,0,0]
	s_waitcnt lgkmcnt(4)
	v_pk_fma_f32 v[124:125], v[124:125], s[52:53], v[12:13] op_sel:[0,0,1] op_sel_hi:[1,0,0]
	v_pk_fma_f32 v[108:109], v[108:109], s[52:53], v[28:29] op_sel:[0,0,1] op_sel_hi:[1,0,0]
	s_waitcnt lgkmcnt(2)
	v_pk_fma_f32 v[126:127], v[126:127], s[52:53], v[14:15] op_sel:[0,0,1] op_sel_hi:[1,0,0]
	v_pk_fma_f32 v[128:129], v[128:129], s[52:53], v[16:17] op_sel:[0,0,1] op_sel_hi:[1,0,0]
	s_waitcnt lgkmcnt(0)
	v_pk_fma_f32 v[112:113], v[112:113], s[52:53], v[30:31] op_sel:[0,0,1] op_sel_hi:[1,0,0]
	v_pk_fma_f32 v[110:111], v[110:111], s[52:53], v[32:33] op_sel:[0,0,1] op_sel_hi:[1,0,0]
	s_mov_b64 s[0:1], 0
	s_branch .LBB0_543

; #define LAS __attribute__((address_space(3)))
; __device__ __forceinline__ float ex2(float x) { return __builtin_amdgcn_exp2f(x); }
; __device__ __forceinline__ v16f mfma32(v8s a, v8s b, v16f c) { return __builtin_amdgcn_mfma_f32_32x32x16_bf16(a, b, c, 0, 0, 0); }
; __device__ __forceinline__ float max3f(float a, float b, float c) { return __builtin_fmaxf(__builtin_fmaxf(a, b), c); }
;     __device__ __forceinline__ bool rowok(int t) const { return ((t < 32 ? (mlo >> t) : (mhi >> (t - 32))) & 1u) != 0u; }
;     __device__ __forceinline__ bool rowok(int t, int sub) const { const unsigned lo = sub ? mloB : mloA, hh = sub ? mhiB : mhiA; return ((t < 32 ? (lo >> t) : (hh >> (t - 32))) & 1u) != 0u; }
; __device__ __forceinline__ void k_load(const LAS unsigned char* Kt, v8s (&kf)[8], int r32, int hi) {
;     const LAS unsigned char* kb = Kt + r32 * KP + hi * 16;
; #pragma unroll
;     for (int s = 0; s < 4; ++s) { kf[2 * s] = *(const LAS v8s*)(kb + s * 32); kf[2 * s + 1] = *(const LAS v8s*)(kb + 32 * KP + s * 32); }
; }
; __device__ __forceinline__ void qk_mma(const v8s (&kf)[8], const v8s (&qf)[4], v16f& p0, v16f& p1) {
;     v16f z;
; #pragma unroll
;     for (int r = 0; r < 16; ++r) z[r] = 0.f;
;     p0 = z; p1 = z;
; #pragma unroll
;     for (int s = 0; s < 4; ++s) { p0 = mfma32(kf[2 * s], qf[s], p0); p1 = mfma32(kf[2 * s + 1], qf[s], p1); }
; }
; __device__ __forceinline__ void softmax_step(v16f& p0, v16f& p1, v16f (&oT)[2], float& m, float& l, bool rowok) {
;     float a = max3f(p0[0], p0[1], p1[0]), b = max3f(p0[2], p0[3], p1[1]); a = max3f(a, p1[2], p1[3]);
; #pragma unroll
;     for (int r = 4; r < 16; r += 4) { a = max3f(a, p0[r], p0[r + 1]); b = max3f(b, p0[r + 2], p0[r + 3]); a = max3f(a, p1[r], p1[r + 1]); b = max3f(b, p1[r + 2], p1[r + 3]); }
;     float mx = fmaxf(a, b);
;     mx = xhalf_max(mx);
;     if (!rowok) mx = -INFINITY;
;     float mn = m;
;     if (__any(mx > m + SM_THR)) {
;         mn = fmaxf(m, mx);
;         const float mu_ = (mn == -INFINITY) ? 0.f : mn;
;         const float alpha = ex2(m - mu_);
;         oT[0] = oT[0] * alpha; oT[1] = oT[1] * alpha; l *= alpha;
;     }
.LBB0_548:
	s_add_i32 s0, s55, 1
	s_cmp_lg_u32 s55, 2
	v_cndmask_b32_e64 v2, 0, 1, s[4:5]
	s_cselect_b32 s54, s0, 0
	v_cmp_ne_u32_e64 s[0:1], 1, v2
	s_andn2_b64 vcc, exec, s[4:5]
	s_cbranch_vccnz .LBB0_550
	s_mul_i32 s4, s54, 0x2400
	v_add_u32_e32 v30, s4, v198
	ds_read_b128 v[218:221], v30
	ds_read_b128 v[222:225], v30 offset:32
	ds_read_b128 v[226:229], v30 offset:4608
	ds_read_b128 v[230:233], v30 offset:4640
	ds_read_b128 v[244:247], v30 offset:64
	ds_read_b128 v[248:251], v30 offset:96
	ds_read_b128 v[208:211], v30 offset:4672
	ds_read_b128 v[212:215], v30 offset:4704
.LBB0_550:
	s_mulk_i32 s55, 0x2080
	v_add_u32_e32 v4, s55, v201
	ds_read_b64_tr_b16 v[22:23], v4 offset:28672
	ds_read_b64_tr_b16 v[24:25], v4 offset:29184
	ds_read_b64_tr_b16 v[14:15], v4 offset:29696
	ds_read_b64_tr_b16 v[16:17], v4 offset:30208
	ds_read_b64_tr_b16 v[18:19], v4 offset:32832
	ds_read_b64_tr_b16 v[20:21], v4 offset:33344
	ds_read_b64_tr_b16 v[10:11], v4 offset:33856
	ds_read_b64_tr_b16 v[12:13], v4 offset:34368
	ds_read_b64_tr_b16 v[26:27], v4 offset:31808
	ds_read_b64_tr_b16 v[28:29], v4 offset:32320
	ds_read_b64_tr_b16 v[6:7], v4 offset:30720
	ds_read_b64_tr_b16 v[8:9], v4 offset:31232
	ds_read_b64_tr_b16 v[30:31], v4 offset:27648
	ds_read_b64_tr_b16 v[32:33], v4 offset:28160
	ds_read_b64_tr_b16 v[2:3], v4 offset:34880
	ds_read_b64_tr_b16 v[4:5], v4 offset:35392
	s_waitcnt lgkmcnt(15)
	v_mfma_f32_32x32x16_bf16 v[66:81], v[218:221], v[130:133], 0
	v_mfma_f32_32x32x16_bf16 v[82:97], v[226:229], v[130:133], 0
	v_sub_co_u32_e64 v154, vcc, s50, 32
	v_lshrrev_b32_e32 v155, s50, v188
	v_lshrrev_b32_e32 v154, v154, v189
	v_cndmask_b32_e32 v154, v154, v155, vcc
	v_and_b32_e32 v154, 1, v154
	v_cmp_eq_u32_e64 s[4:5], 0, v154
	v_max_f32_e32 v154, v115, v115
	v_max_f32_e32 v155, v114, v114
	v_max_f32_e32 v154, v155, v154
	v_max3_f32 v155, v116, v117, v99
	v_max3_f32 v154, v154, v98, v100
	v_max3_f32 v154, v154, v101, v118
	v_max3_f32 v155, v155, v120, v121
	v_max3_f32 v154, v154, v119, v102
	v_max3_f32 v155, v155, v104, v105
	v_mfma_f32_32x32x16_bf16 v[66:81], v[222:225], v[134:137], v[66:81]
	v_max3_f32 v154, v154, v103, v122
	v_max3_f32 v155, v155, v124, v125
	v_max3_f32 v154, v154, v123, v106
	v_max3_f32 v155, v155, v108, v109
	v_max3_f32 v154, v154, v107, v126
	v_max3_f32 v155, v155, v128, v129
	v_mfma_f32_32x32x16_bf16 v[82:97], v[230:233], v[134:137], v[82:97]
	v_max3_f32 v154, v154, v127, v110
	v_max3_f32 v155, v155, v112, v113
	v_max3_f32 v154, v154, v111, v155
	v_mov_b32_e32 v155, v154
	s_nop 1
	v_permlane32_swap_b32_e32 v154, v155
	v_max_f32_e32 v155, v155, v155
	v_max_f32_e32 v154, v154, v154
	v_max_f32_e32 v154, v154, v155
	v_cndmask_b32_e64 v154, v154, v241, s[4:5]
	v_add_f32_e32 v155, 0x41800000, v217
	v_cmp_gt_f32_e32 vcc, v154, v155
	s_cbranch_vccz .LBB0_552
	v_max_f32_e32 v0, v154, v154
	v_max_f32_e32 v154, v217, v217
	v_max_f32_e32 v155, v154, v0
	v_cmp_neq_f32_e32 vcc, s76, v155
	s_nop 1
	v_cndmask_b32_e32 v0, 0, v155, vcc
	v_sub_f32_e32 v154, v217, v0
	v_exp_f32_e32 v154, v154
	v_mov_b32_e32 v217, v155
	v_pk_mul_f32 v[48:49], v[48:49], v[154:155] op_sel_hi:[1,0]
	v_pk_mul_f32 v[46:47], v[46:47], v[154:155] op_sel_hi:[1,0]
	v_pk_mul_f32 v[44:45], v[44:45], v[154:155] op_sel_hi:[1,0]
	v_pk_mul_f32 v[42:43], v[42:43], v[154:155] op_sel_hi:[1,0]
	v_pk_mul_f32 v[40:41], v[40:41], v[154:155] op_sel_hi:[1,0]
	v_pk_mul_f32 v[38:39], v[38:39], v[154:155] op_sel_hi:[1,0]
	v_pk_mul_f32 v[36:37], v[36:37], v[154:155] op_sel_hi:[1,0]
	v_pk_mul_f32 v[34:35], v[34:35], v[154:155] op_sel_hi:[1,0]
	v_pk_mul_f32 v[64:65], v[64:65], v[154:155] op_sel_hi:[1,0]
	v_pk_mul_f32 v[62:63], v[62:63], v[154:155] op_sel_hi:[1,0]
	v_pk_mul_f32 v[60:61], v[60:61], v[154:155] op_sel_hi:[1,0]
	v_pk_mul_f32 v[58:59], v[58:59], v[154:155] op_sel_hi:[1,0]
	v_pk_mul_f32 v[56:57], v[56:57], v[154:155] op_sel_hi:[1,0]
	v_pk_mul_f32 v[54:55], v[54:55], v[154:155] op_sel_hi:[1,0]
	v_pk_mul_f32 v[52:53], v[52:53], v[154:155] op_sel_hi:[1,0]
	v_pk_mul_f32 v[50:51], v[50:51], v[154:155] op_sel_hi:[1,0]
	v_mul_f32_e32 v216, v216, v154
; #define LAS __attribute__((address_space(3)))
; __device__ __forceinline__ v16f mfma32(v8s a, v8s b, v16f c) { return __builtin_amdgcn_mfma_f32_32x32x16_bf16(a, b, c, 0, 0, 0); }
; __device__ __forceinline__ void pv_mma(const v4s (&vf)[16], const v16f& p0, const v16f& p1, v16f (&oT)[2]) {
;     v4u w[4];
;     w[0] = (v4u){pkbf(p0[0], p0[1]), pkbf(p0[2], p0[3]), pkbf(p0[4], p0[5]), pkbf(p0[6], p0[7])};
;     w[1] = (v4u){pkbf(p0[8], p0[9]), pkbf(p0[10], p0[11]), pkbf(p0[12], p0[13]), pkbf(p0[14], p0[15])};
;     w[2] = (v4u){pkbf(p1[0], p1[1]), pkbf(p1[2], p1[3]), pkbf(p1[4], p1[5]), pkbf(p1[6], p1[7])};
;     w[3] = (v4u){pkbf(p1[8], p1[9]), pkbf(p1[10], p1[11]), pkbf(p1[12], p1[13]), pkbf(p1[14], p1[15])};
; #pragma unroll
;     for (int ks = 0; ks < 4; ++ks)
; #pragma unroll
;         for (int dt = 0; dt < 2; ++dt) {
;             const v4s lo = vf[4 * ks + 2 * dt], h4 = vf[4 * ks + 2 * dt + 1];
;             const v8s af = (v8s){lo[0], lo[1], lo[2], lo[3], h4[0], h4[1], h4[2], h4[3]};
;             oT[dt] = mfma32(af, __builtin_bit_cast(v8s, w[ks]), oT[dt]);
;         }
;     __device__ __forceinline__ void apply_tab(v16f& p0, v16f& p1, int t) const {
;         const LAS float* bp = tb + (NEGPAD + qpos - 64 * t - 63 - 4 * hi);
;         v16f c0, c1;
; #pragma unroll
;         for (int r = 0; r < 16; ++r) { c0[r] = bp[63 - ((r & 3) + 8 * (r >> 2))]; c1[r] = bp[31 - ((r & 3) + 8 * (r >> 2))]; }
;         p0 = p0 * C1 + c0; p1 = p1 * C1 + c1;
;     }
.LBB0_552:
	v_cndmask_b32_e64 v0, v0, v240, s[4:5]
	v_sub_f32_e32 v121, v121, v0
	v_sub_f32_e32 v120, v120, v0
	v_sub_f32_e32 v119, v119, v0
	v_sub_f32_e32 v118, v118, v0
	v_sub_f32_e32 v117, v117, v0
	v_sub_f32_e32 v116, v116, v0
	v_sub_f32_e32 v115, v115, v0
	v_sub_f32_e32 v114, v114, v0
	v_exp_f32_e32 v114, v114
	v_exp_f32_e32 v115, v115
	v_exp_f32_e32 v116, v116
	v_exp_f32_e32 v117, v117
	v_exp_f32_e32 v118, v118
	v_exp_f32_e32 v119, v119
	v_exp_f32_e32 v120, v120
	v_exp_f32_e32 v121, v121
	v_sub_f32_e32 v154, v105, v0
	v_sub_f32_e32 v155, v104, v0
	v_sub_f32_e32 v156, v103, v0
	v_sub_f32_e32 v157, v102, v0
	v_cvt_pk_bf16_f32 v102, v114, v115
	v_cvt_pk_bf16_f32 v103, v116, v117
	v_cvt_pk_bf16_f32 v104, v118, v119
	v_cvt_pk_bf16_f32 v105, v120, v121
	v_sub_f32_e32 v129, v129, v0
	v_sub_f32_e32 v128, v128, v0
	s_waitcnt lgkmcnt(2)
	v_mfma_f32_32x32x16_bf16 v[34:49], v[30:33], v[102:105], v[34:49]
	v_sub_f32_e32 v127, v127, v0
	v_sub_f32_e32 v126, v126, v0
	v_sub_f32_e32 v125, v125, v0
	v_sub_f32_e32 v124, v124, v0
	v_mfma_f32_32x32x16_bf16 v[66:81], v[244:247], v[138:141], v[66:81]
	v_sub_f32_e32 v123, v123, v0
	v_sub_f32_e32 v122, v122, v0
	v_exp_f32_e32 v122, v122
	v_mfma_f32_32x32x16_bf16 v[50:65], v[26:29], v[102:105], v[50:65]
	v_exp_f32_e32 v123, v123
	v_exp_f32_e32 v124, v124
	v_exp_f32_e32 v125, v125
	v_exp_f32_e32 v126, v126
	v_exp_f32_e32 v127, v127
	v_mfma_f32_32x32x16_bf16 v[82:97], v[208:211], v[138:141], v[82:97]
	v_exp_f32_e32 v128, v128
	v_exp_f32_e32 v129, v129
	v_cvt_pk_bf16_f32 v26, v122, v123
	v_cvt_pk_bf16_f32 v27, v124, v125
	v_cvt_pk_bf16_f32 v28, v126, v127
	v_cvt_pk_bf16_f32 v29, v128, v129
	v_sub_f32_e32 v30, v101, v0
	v_sub_f32_e32 v31, v100, v0
	v_mfma_f32_32x32x16_bf16 v[34:49], v[22:25], v[26:29], v[34:49]
	v_sub_f32_e32 v22, v99, v0
	v_sub_f32_e32 v23, v98, v0
	v_exp_f32_e32 v98, v23
	v_exp_f32_e32 v99, v22
	v_exp_f32_e32 v100, v31
	v_exp_f32_e32 v101, v30
	v_exp_f32_e32 v102, v157
	v_mfma_f32_32x32x16_bf16 v[50:65], v[18:21], v[26:29], v[50:65]
	v_exp_f32_e32 v103, v156
	v_exp_f32_e32 v104, v155
	v_exp_f32_e32 v105, v154
	v_cvt_pk_bf16_f32 v18, v98, v99
	v_cvt_pk_bf16_f32 v19, v100, v101
	v_cvt_pk_bf16_f32 v20, v102, v103
	v_cvt_pk_bf16_f32 v21, v104, v105
	v_sub_f32_e32 v113, v113, v0
	v_sub_f32_e32 v112, v112, v0
	v_mfma_f32_32x32x16_bf16 v[66:81], v[248:251], v[142:145], v[66:81]
	v_mfma_f32_32x32x16_bf16 v[34:49], v[14:17], v[18:21], v[34:49]
	v_sub_f32_e32 v111, v111, v0
	v_sub_f32_e32 v110, v110, v0
	v_sub_f32_e32 v109, v109, v0
	v_sub_f32_e32 v108, v108, v0
	v_sub_f32_e32 v14, v107, v0
	v_sub_f32_e32 v0, v106, v0
	v_exp_f32_e32 v106, v0
	v_mfma_f32_32x32x16_bf16 v[50:65], v[10:13], v[18:21], v[50:65]
	v_exp_f32_e32 v107, v14
	v_mfma_f32_32x32x16_bf16 v[82:97], v[212:215], v[142:145], v[82:97]
	v_exp_f32_e32 v108, v108
	v_exp_f32_e32 v109, v109
	v_exp_f32_e32 v110, v110
	v_exp_f32_e32 v111, v111
	v_exp_f32_e32 v112, v112
	v_exp_f32_e32 v113, v113
	v_cvt_pk_bf16_f32 v10, v106, v107
	v_cvt_pk_bf16_f32 v11, v108, v109
	v_cvt_pk_bf16_f32 v12, v110, v111
	v_cvt_pk_bf16_f32 v13, v112, v113
	s_and_b64 vcc, exec, s[0:1]
	s_nop 0
	v_mfma_f32_32x32x16_bf16 v[34:49], v[6:9], v[10:13], v[34:49]
	s_waitcnt lgkmcnt(0)
	v_mfma_f32_32x32x16_bf16 v[50:65], v[2:5], v[10:13], v[50:65]
	s_cbranch_vccnz .LBB0_558
	s_lshl_b32 s4, s26, 6
	s_sub_i32 s0, s49, s4
	s_cmpk_lt_i32 s0, 0x400
	s_mov_b64 s[0:1], -1
	s_cbranch_scc0 .LBB0_555
	v_add_u32_e32 v0, s4, v200
	v_sub_u32_e32 v0, v199, v0
	v_lshl_add_u32 v0, v0, 2, s37
	v_add_u32_e32 v0, 0xd110, v0
	ds_read2_b32 v[2:3], v0 offset0:58 offset1:59
	ds_read2_b32 v[154:155], v0 offset0:26 offset1:27
	ds_read2_b32 v[4:5], v0 offset0:56 offset1:57
	ds_read2_b32 v[20:21], v0 offset0:24 offset1:25
	ds_read2_b32 v[6:7], v0 offset0:50 offset1:51
	ds_read2_b32 v[22:23], v0 offset0:18 offset1:19
	ds_read2_b32 v[8:9], v0 offset0:48 offset1:49
	ds_read2_b32 v[24:25], v0 offset0:16 offset1:17
	ds_read2_b32 v[10:11], v0 offset0:42 offset1:43
	ds_read2_b32 v[26:27], v0 offset0:10 offset1:11
	ds_read2_b32 v[12:13], v0 offset0:40 offset1:41
	ds_read2_b32 v[28:29], v0 offset0:8 offset1:9
	ds_read2_b32 v[14:15], v0 offset0:34 offset1:35
	ds_read2_b32 v[16:17], v0 offset0:32 offset1:33
	ds_read2_b32 v[30:31], v0 offset0:0 offset1:1
	ds_read2_b32 v[32:33], v0 offset0:2 offset1:3
	s_waitcnt lgkmcnt(14)
	v_pk_fma_f32 v[66:67], v[66:67], s[52:53], v[2:3] op_sel:[0,0,1] op_sel_hi:[1,0,0]
	v_pk_fma_f32 v[82:83], v[82:83], s[52:53], v[154:155] op_sel:[0,0,1] op_sel_hi:[1,0,0]
	s_waitcnt lgkmcnt(12)
	v_pk_fma_f32 v[68:69], v[68:69], s[52:53], v[4:5] op_sel:[0,0,1] op_sel_hi:[1,0,0]
	v_pk_fma_f32 v[84:85], v[84:85], s[52:53], v[20:21] op_sel:[0,0,1] op_sel_hi:[1,0,0]
	s_waitcnt lgkmcnt(10)
	v_pk_fma_f32 v[70:71], v[70:71], s[52:53], v[6:7] op_sel:[0,0,1] op_sel_hi:[1,0,0]
	v_pk_fma_f32 v[86:87], v[86:87], s[52:53], v[22:23] op_sel:[0,0,1] op_sel_hi:[1,0,0]
	s_waitcnt lgkmcnt(8)
	v_pk_fma_f32 v[72:73], v[72:73], s[52:53], v[8:9] op_sel:[0,0,1] op_sel_hi:[1,0,0]
	v_pk_fma_f32 v[88:89], v[88:89], s[52:53], v[24:25] op_sel:[0,0,1] op_sel_hi:[1,0,0]
	s_waitcnt lgkmcnt(6)
	v_pk_fma_f32 v[74:75], v[74:75], s[52:53], v[10:11] op_sel:[0,0,1] op_sel_hi:[1,0,0]
	v_pk_fma_f32 v[90:91], v[90:91], s[52:53], v[26:27] op_sel:[0,0,1] op_sel_hi:[1,0,0]
	s_waitcnt lgkmcnt(4)
	v_pk_fma_f32 v[76:77], v[76:77], s[52:53], v[12:13] op_sel:[0,0,1] op_sel_hi:[1,0,0]
	v_pk_fma_f32 v[92:93], v[92:93], s[52:53], v[28:29] op_sel:[0,0,1] op_sel_hi:[1,0,0]
	s_waitcnt lgkmcnt(2)
	v_pk_fma_f32 v[78:79], v[78:79], s[52:53], v[14:15] op_sel:[0,0,1] op_sel_hi:[1,0,0]
	v_pk_fma_f32 v[80:81], v[80:81], s[52:53], v[16:17] op_sel:[0,0,1] op_sel_hi:[1,0,0]
	s_waitcnt lgkmcnt(0)
	v_pk_fma_f32 v[96:97], v[96:97], s[52:53], v[30:31] op_sel:[0,0,1] op_sel_hi:[1,0,0]
	v_pk_fma_f32 v[94:95], v[94:95], s[52:53], v[32:33] op_sel:[0,0,1] op_sel_hi:[1,0,0]
	s_mov_b64 s[0:1], 0
	s_branch .LBB0_558
